# grid barrier: all workgroups poll one global arrival counter (TOP >= (gen+1)*nXCD); XCD leaders add with a non-returning atomic; TOPGEN relay and per-XCD generation words no longer on the release path
# speedup vs baseline: 1.0053x; 1.0008x over previous
.LBB0_942:
	s_or_b64 exec, exec, s[6:7]
	v_cvt_f32_u32_e32 v5, v3
	s_waitcnt vmcnt(0)
	v_readfirstlane_b32 s4, v4
	v_sub_u32_e32 v4, 0, v3
	v_rcp_iflag_f32_e32 v5, v5
	v_add_u32_e32 v6, s4, v0
	v_mul_f32_e32 v5, 0x4f7ffffe, v5
	v_cvt_u32_f32_e32 v5, v5
	v_mul_lo_u32 v0, v4, v5
	v_mul_hi_u32 v0, v5, v0
	v_add_u32_e32 v0, v5, v0
	v_mul_hi_u32 v0, v6, v0
	v_mul_lo_u32 v4, v0, v3
	v_sub_u32_e32 v4, v6, v4
	v_add_u32_e32 v5, 1, v0
	v_cmp_ge_u32_e32 vcc, v4, v3
	s_nop 1
	v_cndmask_b32_e32 v0, v0, v5, vcc
	v_sub_u32_e32 v5, v4, v3
	v_cndmask_b32_e32 v4, v4, v5, vcc
	v_add_u32_e32 v5, 1, v0
	v_cmp_ge_u32_e32 vcc, v4, v3
	v_add_u32_e32 v4, 1, v6
	s_nop 0
	v_cndmask_b32_e32 v0, v0, v5, vcc
	v_mul_lo_u32 v5, v3, v0
	v_add_u32_e32 v3, v5, v3
	v_cmp_ne_u32_e32 vcc, v4, v3
	s_and_saveexec_b64 s[4:5], vcc
	s_xor_b64 s[4:5], exec, s[4:5]
	s_cbranch_execz .LBB0_957
	s_waitcnt lgkmcnt(0)
	buffer_inv sc1
	v_add_u32_e32 v5, 1, v0
	v_mul_lo_u32 v5, v5, v2
	v_mov_b32_e32 v6, 0x1efc3000
.Lxn_poll:
	global_load_dword v4, v6, s[54:55] offset:1024 sc1
	s_waitcnt vmcnt(0)
	v_cmp_lt_u32_e32 vcc, v4, v5
	s_cbranch_vccz .Lxn_done
	s_sleep 1
	s_branch .Lxn_poll
.Lxn_done:
	s_branch .LBB0_957
.LBB0_952:
	s_mov_b64 s[6:7], 0x11f80000
	s_movk_i32 s18, 0xb00
	s_cbranch_execz .LBB0_893
	s_branch .LBB0_894
.LBB0_957:
	s_andn2_saveexec_b64 s[4:5], s[4:5]
	s_cbranch_execnz .LBB0_958
	s_getpc_b64 s[98:99]

.LBB0_958:
	buffer_wbl2 sc1
	s_waitcnt vmcnt(0) lgkmcnt(0)
	v_add_u32_e32 v5, 1, v0
	v_mul_lo_u32 v5, v5, v2
	v_mov_b32_e32 v6, 0x1efc3000
	global_atomic_add v6, v212, s[54:55] offset:1024

.Lxl_done:
	buffer_inv sc1
	s_mov_b64 s[6:7], 0
	s_getpc_b64 s[98:99]
